# attention stride-1 tiles: ALiBi term slope2*k read from a per-wave LDS table into the score accumulators as MFMA C input instead of 32 VALU FMAs per tile (unmasked window and selected bodies)
# baseline (speedup 1.0000x reference)
; DI void hsync() { hsync_impl(false); }
; DI float fexp2(float x) { return __builtin_amdgcn_exp2f(x); }
; DI void attn_item(const Params& p, int item, char* smem) {
;     ...
;   bf16x8 qf[4];
; #pragma unroll
;   for (int ks = 0; ks < 4; ++ks) qf[ks] = *(const bf16x8*)(Q + row * 512 + head * 64 + ks * 16 + hh * 8);
;   float* ot_s = (float*)(sel8 + 256) + wave * 32 * 64 + lane;
;   const float slope2 = fexp2(-(float)(head + 1)) * LOG2E;
;   const float gc = NG[row * 32 + head], gs = NG[row * 32 + 8 + head], gw = NG[row * 32 + 16 + head];
;   f32x16 O[2];
;   hsync();
;   for (int i = tid; i < 32 * 65; i += 256) imp_s[i] = 0u;
;   const int nct = t0 / 1024 + 1;
;   float m = -1e30f, l = 0.f;
;   KVRegs kvr;
;   kv_issue(kvr, KCMP + ((size_t)(bg * 256)) * 64, 64, VCMPT + (size_t)bg * 64 * 256, 256, tid);
.LBB0_546:
	s_or_b64 exec, exec, s[0:1]
	s_and_b32 s8, s79, 7
	v_lshlrev_b32_e32 v2, 3, v130
	s_lshr_b32 s86, s57, 10
	s_lshl_b32 s88, s8, 8
	s_lshl_b32 s9, s8, 15
	v_readlane_b32 s10, v252, 3
	v_and_b32_e32 v100, 56, v2
	v_add_u32_e32 v2, 0x100, v130
	v_readlane_b32 s11, v252, 4
	s_add_u32 s0, s10, s9
	v_ashrrev_i32_e32 v112, 3, v130
	v_ashrrev_i32_e32 v114, 3, v2
	s_addc_u32 s1, s11, 0
	s_lshl_b32 s91, s8, 6
	v_ashrrev_i32_e32 v113, 31, v112
	v_ashrrev_i32_e32 v115, 31, v114
	v_lshlrev_b32_e32 v2, 1, v100
	v_mov_b32_e32 v3, v97
	s_add_u32 s8, s62, s9
	v_lshl_add_u64 v[4:5], s[0:1], 0, v[2:3]
	v_lshlrev_b64 v[102:103], 7, v[112:113]
	v_lshlrev_b64 v[104:105], 7, v[114:115]
	s_addc_u32 s9, s63, 0
	v_lshl_add_u64 v[6:7], v[4:5], 0, v[102:103]
	v_lshl_add_u64 v[4:5], v[4:5], 0, v[104:105]
	global_load_dwordx4 v[80:83], v[6:7], off
	global_load_dwordx4 v[88:91], v[4:5], off
	v_lshl_add_u64 v[116:117], s[8:9], 0, v[2:3]
	v_lshlrev_b64 v[4:5], 9, v[112:113]
	v_lshl_add_u64 v[4:5], v[116:117], 0, v[4:5]
	v_lshlrev_b64 v[6:7], 9, v[114:115]
	v_lshl_add_u64 v[6:7], v[116:117], 0, v[6:7]
	global_load_dwordx4 v[84:87], v[4:5], off
	global_load_dwordx4 v[92:95], v[6:7], off
	v_add_u32_e32 v0, 1, v0
	v_cvt_f32_i32_e32 v0, v0
	s_movk_i32 s0, 0x48
	v_lshlrev_b64 v[118:119], 6, v[112:113]
	v_lshlrev_b64 v[108:109], 8, v[112:113]
	v_exp_f32_e64 v0, -v0
	v_lshlrev_b64 v[120:121], 6, v[114:115]
	v_lshlrev_b64 v[110:111], 8, v[114:115]
	v_mul_lo_u32 v158, v112, s0
	v_mul_f32_e32 v106, 0x3fb8aa3b, v0
	v_mbcnt_lo_u32_b32 v239, -1, 0
	v_mbcnt_hi_u32_b32 v239, -1, v239
	v_sub_u32_e32 v238, v249, v250
	v_cvt_f32_u32_e32 v240, v239
	v_lshl_add_u32 v238, v238, 6, v250
	v_add_u32_e32 v238, 0xfffff9a0, v238
	v_mul_f32_e32 v240, v106, v240
	v_lshl_add_u32 v241, v239, 2, v238
	ds_write_b32 v241, v240
	v_mul_u32_u24_e32 v0, 0x48, v129
	v_mul_lo_u32 v159, v114, s0
	v_mul_i32_i24_e32 v135, 0xffffffc0, v128
	v_subrev_u32_e32 v136, 31, v157
	v_lshl_add_u64 v[122:123], s[10:11], 0, v[2:3]
	v_mov_b32_e32 v160, 0xf149f2ca
	s_mov_b32 s79, 0
	v_mov_b32_e32 v32, 0
	v_lshlrev_b32_e32 v161, 1, v1
	v_lshlrev_b32_e32 v162, 1, v0
	s_mov_b32 s80, 0
	v_mov_b32_e32 v33, 0xf149f2ca

; #define MFMA32(a, b, c) __builtin_amdgcn_mfma_f32_32x32x16_bf16((a), (b), (c), 0, 0, 0)
; template <int KSTRIDE, bool WIN, int MASK, int MODE>
; DI void attend_tile(const u16* Ks, const u16* Vts, const bf16x8 (&qf)[4], f32x16 (&O)[2], float& m, float& l, int dbase,
;                     float slope2, bool lanesel, float invl, unsigned* imp_row, int mbase, int lr, int hh) {
;     ...
;   for (int kt = 0; kt < 2; ++kt) {
; #pragma unroll
;     for (int e = 0; e < 16; ++e) s[kt][e] = 0.f;
; #pragma unroll
;     for (int ks = 0; ks < 4; ++ks) {
;       bf16x8 a = *(const bf16x8*)(Ks + (kt * 32 + lr) * 72 + ks * 16 + hh * 8);
;       s[kt] = MFMA32(a, qf[ks], s[kt]);
;     }
;   }
;   const float fd0 = (float)(dbase - KSTRIDE * 4 * hh);
;   const float ct = slope2 * fd0;
;   float mx = -1e30f;
; #pragma unroll
;   for (int kt = 0; kt < 2; ++kt)
; #pragma unroll
;     for (int e = 0; e < 16; ++e) {
;       const float Ke = (float)(KSTRIDE * (kt * 32 + (e & 3) + 8 * (e >> 2)));
;       float v = fmaf(slope2, Ke, s[kt][e]);
;       if (MASK == 1) {
;         const float fd = fd0 - Ke;
;         bool valid = fd >= 0.f;
;         if (WIN) valid = valid && (fd < 512.f);
;         valid = valid && lanesel;
;         v = valid ? v : -1e30f;
;       }
;       s[kt][e] = v;
;       mx = fmaxf(mx, v);
;     }
;   mx = (mx > -1e29f) ? mx - ct : -1e30f;
;   mx = fmaxf(mx, __shfl_xor(mx, 32));
;   if (MASK == 2) mx = lanesel ? mx : -1e30f;
; DI void attn_item(const Params& p, int item, char* smem) {
;     ...
;     for (int i = i0; i < 9; ++i) {
;       const int k0 = kbase + 64 * i;
;       kv_commit(kvr, Ks, Vts, tid);
;       if (i + 1 < 9) kv_issue(kvr, KW + ((size_t)(b * 4096 + k0 + 64)) * 128 + g * 64, 128, VTW + (size_t)bg * 64 * 4096 + k0 + 64, 4096, tid);
;       if (i >= 1 && i <= 7) attend_tile<1, false, 0, 0>(Ks, Vts, qf, O, m, l, t - k0, slope2, true, 0.f, nullptr, 0, lr, hh);
;       else attend_tile<1, true, 1, 0>(Ks, Vts, qf, O, m, l, t - k0, slope2, true, 0.f, nullptr, 0, lr, hh);
.LBB0_623:
	v_add3_u32 v144, s38, v161, v162
	s_waitcnt lgkmcnt(8)
	ds_read_b128 v[80:83], v144
	s_waitcnt lgkmcnt(8)
	ds_read_b128 v[60:63], v144 offset:32
	s_waitcnt lgkmcnt(8)
	ds_read_b128 v[56:59], v144 offset:64
	s_waitcnt lgkmcnt(8)
	ds_read_b128 v[48:51], v144 offset:96
	s_waitcnt lgkmcnt(8)
	ds_read_b128 v[52:55], v144 offset:4608
	s_and_b32 s0, s89, 7
	s_cmp_eq_u32 s0, 0
	s_cbranch_scc1 .LBB0_628
	ds_read_b128 v[16:19], v238 offset:0
	ds_read_b128 v[20:23], v238 offset:32
	ds_read_b128 v[24:27], v238 offset:64
	ds_read_b128 v[28:31], v238 offset:96
	ds_read_b128 v[0:3], v238 offset:128
	ds_read_b128 v[4:7], v238 offset:160
	ds_read_b128 v[8:11], v238 offset:192
	ds_read_b128 v[12:15], v238 offset:224
	s_waitcnt lgkmcnt(4)
	v_mfma_f32_32x32x16_bf16 v[16:31], v[80:83], v[64:67], v[16:31]
	ds_read_b128 v[84:87], v144 offset:4640
	ds_read_b128 v[146:149], v144 offset:4672
	s_waitcnt lgkmcnt(5)
	v_mfma_f32_32x32x16_bf16 v[16:31], v[60:63], v[68:71], v[16:31]
	s_waitcnt lgkmcnt(2)
	v_mfma_f32_32x32x16_bf16 v[0:15], v[52:55], v[64:67], v[0:15]
	v_mfma_f32_32x32x16_bf16 v[16:31], v[56:59], v[72:75], v[16:31]
	s_waitcnt lgkmcnt(1)
	v_mfma_f32_32x32x16_bf16 v[0:15], v[84:87], v[68:71], v[0:15]
	ds_read_b128 v[84:87], v144 offset:4704
	v_mfma_f32_32x32x16_bf16 v[16:31], v[48:51], v[76:79], v[16:31]
	s_waitcnt lgkmcnt(1)
	v_mfma_f32_32x32x16_bf16 v[0:15], v[146:149], v[72:75], v[0:15]
	s_nop 9
	s_nop 0
	s_nop 0
	s_nop 0
	s_nop 0
	s_nop 0
	s_nop 0
	s_nop 0
	s_waitcnt lgkmcnt(0)
	v_mfma_f32_32x32x16_bf16 v[0:15], v[84:87], v[76:79], v[0:15]
	ds_read_b128 v[200:203], v144 offset:9216
	ds_read_b128 v[204:207], v144 offset:13824
	ds_read_b128 v[214:217], v144 offset:9248
	ds_read_b128 v[218:221], v144 offset:13856
	ds_read_b128 v[222:225], v144 offset:9280
	ds_read_b128 v[226:229], v144 offset:13888
	ds_read_b128 v[230:233], v144 offset:9312
	ds_read_b128 v[234:237], v144 offset:13920
	v_max3_f32 v85, v16, s95, v17
	v_max3_f32 v85, v85, v18, v19
	v_max3_f32 v85, v85, v20, v21
	s_nop 0
	v_max3_f32 v85, v85, v22, v23
	s_nop 0
	s_nop 0
	v_max3_f32 v85, v85, v24, v25
	s_nop 0
	s_nop 0
	v_max3_f32 v85, v85, v26, v27
	s_nop 0
	s_nop 0
	v_max3_f32 v85, v85, v28, v29
	s_nop 0
	s_nop 0
	v_max3_f32 v85, v85, v30, v31
	s_nop 0
	s_nop 0
	v_max3_f32 v85, v85, v0, v1
	s_nop 0
	s_nop 0
	v_max3_f32 v85, v85, v2, v3
	s_nop 0
	s_nop 0
	v_or_b32_e32 v84, s8, v116
	v_max3_f32 v85, v85, v4, v5
	s_nop 0
	s_nop 0
	v_sub_u32_e32 v84, v157, v84
	v_max3_f32 v85, v85, v6, v7
	s_nop 0
	s_nop 0
	v_cvt_f32_i32_e32 v84, v84
	v_max3_f32 v85, v85, v8, v9
	s_nop 0
	s_nop 0
	v_max3_f32 v85, v85, v10, v11
	s_nop 0
	s_nop 0
	v_max3_f32 v85, v85, v12, v13
	s_nop 0
	s_nop 0
	v_max3_f32 v85, v85, v14, v15
	v_cmp_lt_f32_e32 vcc, s76, v85
	v_fma_f32 v85, -v106, v84, v85
	s_nop 0
	v_cndmask_b32_e32 v85, v160, v85, vcc
	v_mov_b32_e32 v86, v85
	s_nop 1
	v_permlane32_swap_b32_e32 v86, v85
	s_nop 1
	s_waitcnt lgkmcnt(0)
; #define MFMA32(a, b, c) __builtin_amdgcn_mfma_f32_32x32x16_bf16((a), (b), (c), 0, 0, 0)
; DI float fexp2(float x) { return __builtin_amdgcn_exp2f(x); }
; template <int KSTRIDE, bool WIN, int MASK, int MODE>
; DI void attend_tile(const u16* Ks, const u16* Vts, const bf16x8 (&qf)[4], f32x16 (&O)[2], float& m, float& l, int dbase,
;                     float slope2, bool lanesel, float invl, unsigned* imp_row, int mbase, int lr, int hh) {
;     ...
;   float shift = mnew + ct;
;   if (MASK == 2) shift = lanesel ? shift : 1e30f;
;   float rs = 0.f;
; #pragma unroll
;   for (int kt = 0; kt < 2; ++kt)
; #pragma unroll
;     for (int e = 0; e < 16; ++e) {
;       float v = s[kt][e];
;       float pv;
;       if (MASK == 1) pv = (v > -1e29f) ? fexp2(v - shift) : 0.f;
;       else pv = fexp2(v - shift);
;       if (MODE == 2) pv *= invl;
;       s[kt][e] = pv;
;       rs += pv;
;     }
;   if (MODE != 2) l = l * alpha + rs;
;   if (MODE == 1) return;
;   if (MODE == 0) {
; #pragma unroll
;     for (int e = 0; e < 16; ++e) { O[0][e] *= alpha; O[1][e] *= alpha; }
;   }
;   if (MODE == 2) {
; #pragma unroll
;     for (int kt = 0; kt < 2; ++kt)
; #pragma unroll
;       for (int q4 = 0; q4 < 4; ++q4) {
;         float qsum = s[kt][q4 * 4] + s[kt][q4 * 4 + 1] + s[kt][q4 * 4 + 2] + s[kt][q4 * 4 + 3];
;         float last = s[kt][q4 * 4 + 3];
;         int mi = mbase + kt * 8 + 2 * q4 + hh;
;         atomicAdd(imp_row + mi, (unsigned)(qsum * 1048576.f + 0.5f));
;         if (mi + 1 < 64) atomicAdd(imp_row + mi + 1, (unsigned)(last * 1048576.f + 0.5f));
;       }
;   }
; #pragma unroll
;   for (int kt = 0; kt < 2; ++kt)
; #pragma unroll
;     for (int sx = 0; sx < 2; ++sx) {
;       unsigned pk[4];
; #pragma unroll
;       for (int q = 0; q < 4; ++q) pk[q] = pack2(s[kt][8 * sx + 2 * q], s[kt][8 * sx + 2 * q + 1]);
;       bf16x8 pb;
;       {
;         u32x4 t4 = {pk[0], pk[1], pk[2], pk[3]};
;         pb = __builtin_bit_cast(bf16x8, t4);
;       }
; #pragma unroll
;       for (int dt = 0; dt < 2; ++dt) {
;         bf16x8 a = *(const bf16x8*)(Vts + (dt * 32 + lr) * 72 + kt * 32 + 16 * sx + 8 * hh);
;         O[dt] = MFMA32(a, pb, O[dt]);
;       }
;     }
	v_max3_f32 v145, v143, v85, v86
	v_fma_f32 v84, v106, v84, v145
	v_sub_f32_e32 v16, v16, v84
	v_exp_f32_e32 v86, v16
	v_sub_f32_e32 v17, v17, v84
	v_exp_f32_e32 v87, v17
	v_sub_f32_e32 v17, v18, v84
	v_exp_f32_e32 v181, v17
	v_sub_f32_e32 v17, v19, v84
	v_exp_f32_e32 v182, v17
	v_sub_f32_e32 v17, v20, v84
	v_add_f32_e32 v16, 0, v86
	v_exp_f32_e32 v183, v17
	v_sub_f32_e32 v17, v21, v84
	v_add_f32_e32 v16, v87, v16
	v_exp_f32_e32 v184, v17
	v_sub_f32_e32 v17, v22, v84
	v_sub_f32_e32 v1, v1, v84
	v_add_f32_e32 v16, v181, v16
	v_exp_f32_e32 v185, v17
	v_sub_f32_e32 v17, v23, v84
	v_exp_f32_e32 v148, v1
	v_sub_f32_e32 v1, v2, v84
	v_add_f32_e32 v16, v182, v16
	v_exp_f32_e32 v186, v17
	v_sub_f32_e32 v17, v24, v84
	v_exp_f32_e32 v149, v1
	v_sub_f32_e32 v1, v3, v84
	v_add_f32_e32 v16, v183, v16
	v_exp_f32_e32 v172, v17
	v_sub_f32_e32 v17, v25, v84
	v_exp_f32_e32 v150, v1
	v_sub_f32_e32 v1, v4, v84
	v_add_f32_e32 v16, v184, v16
	v_exp_f32_e32 v174, v17
	v_sub_f32_e32 v17, v26, v84
	v_exp_f32_e32 v151, v1
	v_sub_f32_e32 v1, v5, v84
	v_add_f32_e32 v16, v185, v16
	v_exp_f32_e32 v175, v17
	v_sub_f32_e32 v17, v27, v84
	v_exp_f32_e32 v152, v1
	v_sub_f32_e32 v1, v6, v84
	v_add_f32_e32 v16, v186, v16
	v_exp_f32_e32 v176, v17
	v_sub_f32_e32 v17, v28, v84
	v_exp_f32_e32 v153, v1
	v_sub_f32_e32 v1, v7, v84
	v_add_f32_e32 v16, v172, v16
	v_exp_f32_e32 v177, v17
	v_sub_f32_e32 v17, v29, v84
	v_exp_f32_e32 v165, v1
	v_sub_f32_e32 v1, v8, v84
	v_add_f32_e32 v16, v174, v16
	v_exp_f32_e32 v178, v17
	v_sub_f32_e32 v17, v30, v84
	v_exp_f32_e32 v164, v1
	v_sub_f32_e32 v1, v9, v84
	v_add_f32_e32 v16, v175, v16
	v_exp_f32_e32 v179, v17
	v_sub_f32_e32 v17, v31, v84
	v_exp_f32_e32 v166, v1
	v_sub_f32_e32 v1, v10, v84
	v_add_f32_e32 v16, v176, v16
	v_exp_f32_e32 v180, v17
	v_sub_f32_e32 v0, v0, v84
	v_exp_f32_e32 v167, v1
	v_sub_f32_e32 v1, v11, v84
	v_add_f32_e32 v16, v177, v16
	v_exp_f32_e32 v147, v0
	v_exp_f32_e32 v168, v1
	v_sub_f32_e32 v1, v12, v84
	v_add_f32_e32 v16, v178, v16
	v_exp_f32_e32 v169, v1
	v_sub_f32_e32 v1, v13, v84
	v_sub_f32_e32 v85, v143, v145
	v_add_f32_e32 v16, v179, v16
	v_exp_f32_e32 v170, v1
	v_sub_f32_e32 v1, v14, v84
	v_add_f32_e32 v16, v180, v16
	v_exp_f32_e32 v171, v1
	v_sub_f32_e32 v1, v15, v84
	v_exp_f32_e32 v14, v85
	v_cvt_pk_bf16_f32 v84, v86, v87
	v_cvt_pk_bf16_f32 v85, v181, v182
	v_cvt_pk_bf16_f32 v86, v183, v184
	v_cvt_pk_bf16_f32 v87, v185, v186
	s_nop 0
	v_add_f32_e32 v0, v147, v16
	v_add_f32_e32 v0, v148, v0
	v_add_f32_e32 v0, v149, v0
	v_add_f32_e32 v0, v150, v0
	v_add_f32_e32 v0, v151, v0
	v_add_f32_e32 v0, v152, v0
	v_add_f32_e32 v0, v153, v0
	v_add_f32_e32 v0, v165, v0
	v_pk_mul_f32 v[16:17], v[108:109], v[14:15] op_sel_hi:[1,0]
	v_pk_mul_f32 v[18:19], v[110:111], v[14:15] op_sel_hi:[1,0]
	v_pk_mul_f32 v[20:21], v[112:113], v[14:15] op_sel_hi:[1,0]
	v_pk_mul_f32 v[22:23], v[114:115], v[14:15] op_sel_hi:[1,0]
	v_pk_mul_f32 v[24:25], v[118:119], v[14:15] op_sel_hi:[1,0]
	v_pk_mul_f32 v[26:27], v[120:121], v[14:15] op_sel_hi:[1,0]
	v_pk_mul_f32 v[28:29], v[122:123], v[14:15] op_sel_hi:[1,0]
	v_pk_mul_f32 v[30:31], v[124:125], v[14:15] op_sel_hi:[1,0]
	v_add_f32_e32 v0, v164, v0
	v_add_f32_e32 v0, v166, v0
	s_waitcnt lgkmcnt(0)
	v_mfma_f32_32x32x16_bf16 v[16:31], v[200:203], v[84:87], v[16:31]
	s_nop 0
	v_add_f32_e32 v0, v167, v0
	v_add_f32_e32 v0, v168, v0
	v_exp_f32_e32 v173, v1
	v_add_f32_e32 v0, v169, v0
	v_add_f32_e32 v0, v170, v0
	v_add_f32_e32 v0, v171, v0
	v_add_f32_e32 v146, v173, v0
	v_fmac_f32_e32 v146, v142, v14
	v_pk_mul_f32 v[0:1], v[132:133], v[14:15] op_sel_hi:[1,0]
	v_pk_mul_f32 v[2:3], v[134:135], v[14:15] op_sel_hi:[1,0]
	v_pk_mul_f32 v[4:5], v[138:139], v[14:15] op_sel_hi:[1,0]
	v_pk_mul_f32 v[6:7], v[126:127], v[14:15] op_sel_hi:[1,0]
	v_pk_mul_f32 v[8:9], v[128:129], v[14:15] op_sel_hi:[1,0]
	v_pk_mul_f32 v[10:11], v[130:131], v[14:15] op_sel_hi:[1,0]
	v_pk_mul_f32 v[12:13], v[136:137], v[14:15] op_sel_hi:[1,0]
	v_pk_mul_f32 v[14:15], v[140:141], v[14:15] op_sel_hi:[1,0]
	s_waitcnt lgkmcnt(0)
	s_nop 0
	v_mfma_f32_32x32x16_bf16 v[0:15], v[204:207], v[84:87], v[0:15]
	v_cvt_pk_bf16_f32 v84, v172, v174
	v_cvt_pk_bf16_f32 v85, v175, v176
	v_cvt_pk_bf16_f32 v86, v177, v178
	s_nop 0
	v_cvt_pk_bf16_f32 v87, v179, v180
	s_waitcnt lgkmcnt(0)
	s_nop 0
	v_mfma_f32_32x32x16_bf16 v[16:31], v[214:217], v[84:87], v[16:31]
	s_nop 0
	s_waitcnt lgkmcnt(0)
	v_mfma_f32_32x32x16_bf16 v[0:15], v[218:221], v[84:87], v[0:15]
	v_cvt_pk_bf16_f32 v84, v147, v148
	v_cvt_pk_bf16_f32 v85, v149, v150
	v_cvt_pk_bf16_f32 v86, v151, v152
	s_nop 0
	v_cvt_pk_bf16_f32 v87, v153, v165
	s_waitcnt lgkmcnt(0)
	s_nop 0
	v_mfma_f32_32x32x16_bf16 v[16:31], v[222:225], v[84:87], v[16:31]
	s_nop 0
	s_waitcnt lgkmcnt(0)
	v_mfma_f32_32x32x16_bf16 v[0:15], v[226:229], v[84:87], v[0:15]
	s_nop 0
	v_cvt_pk_bf16_f32 v84, v164, v166
	v_cvt_pk_bf16_f32 v85, v167, v168
	v_cvt_pk_bf16_f32 v86, v169, v170
	v_cvt_pk_bf16_f32 v87, v171, v173
	s_waitcnt lgkmcnt(0)
	s_nop 0
	v_mfma_f32_32x32x16_bf16 v[16:31], v[230:233], v[84:87], v[16:31]
	s_nop 0
	s_waitcnt lgkmcnt(0)
	v_mfma_f32_32x32x16_bf16 v[0:15], v[234:237], v[84:87], v[0:15]
	s_nop 7
	s_nop 3
	s_cbranch_execnz .LBB0_626

; #define MFMA32(a, b, c) __builtin_amdgcn_mfma_f32_32x32x16_bf16((a), (b), (c), 0, 0, 0)
; template <int KSTRIDE, bool WIN, int MASK, int MODE>
; DI void attend_tile(const u16* Ks, const u16* Vts, const bf16x8 (&qf)[4], f32x16 (&O)[2], float& m, float& l, int dbase,
;                     float slope2, bool lanesel, float invl, unsigned* imp_row, int mbase, int lr, int hh) {
;     ...
;   for (int kt = 0; kt < 2; ++kt) {
; #pragma unroll
;     for (int e = 0; e < 16; ++e) s[kt][e] = 0.f;
; #pragma unroll
;     for (int ks = 0; ks < 4; ++ks) {
;       bf16x8 a = *(const bf16x8*)(Ks + (kt * 32 + lr) * 72 + ks * 16 + hh * 8);
;       s[kt] = MFMA32(a, qf[ks], s[kt]);
;     }
;   }
;   const float fd0 = (float)(dbase - KSTRIDE * 4 * hh);
;   const float ct = slope2 * fd0;
;   float mx = -1e30f;
; #pragma unroll
;   for (int kt = 0; kt < 2; ++kt)
; #pragma unroll
;     for (int e = 0; e < 16; ++e) {
;       const float Ke = (float)(KSTRIDE * (kt * 32 + (e & 3) + 8 * (e >> 2)));
;       float v = fmaf(slope2, Ke, s[kt][e]);
;       if (MASK == 1) {
;         const float fd = fd0 - Ke;
;         bool valid = fd >= 0.f;
;         if (WIN) valid = valid && (fd < 512.f);
;         valid = valid && lanesel;
;         v = valid ? v : -1e30f;
;       }
;       s[kt][e] = v;
;       mx = fmaxf(mx, v);
;     }
;   mx = (mx > -1e29f) ? mx - ct : -1e30f;
;   mx = fmaxf(mx, __shfl_xor(mx, 32));
;   if (MASK == 2) mx = lanesel ? mx : -1e30f;
; DI void attn_item(const Params& p, int item, char* smem) {
;     ...
;       bool ls = (j < 32) ? ((mylo >> j) & 1u) : ((myhi >> (j - 32)) & 1u);
;       if (j < qb) attend_tile<1, false, 2, 0>(Ks, Vts, qf, O, m, l, t - 64 * j, slope2, ls, 0.f, nullptr, 0, lr, hh);
.LBB0_644:
	s_andn2_b64 vcc, exec, vcc
	s_cbranch_vccnz .LBB0_646
	ds_read_b128 v[16:19], v238 offset:0
	ds_read_b128 v[20:23], v238 offset:32
	ds_read_b128 v[24:27], v238 offset:64
	ds_read_b128 v[28:31], v238 offset:96
	ds_read_b128 v[0:3], v238 offset:128
	ds_read_b128 v[4:7], v238 offset:160
	ds_read_b128 v[8:11], v238 offset:192
	ds_read_b128 v[12:15], v238 offset:224
	s_waitcnt lgkmcnt(4)
	v_mfma_f32_32x32x16_bf16 v[16:31], v[48:51], v[64:67], v[16:31]
	s_lshl_b32 s80, s80, 6
	s_waitcnt lgkmcnt(3)
	v_mfma_f32_32x32x16_bf16 v[16:31], v[44:47], v[68:71], v[16:31]
	s_waitcnt lgkmcnt(2)
	v_mfma_f32_32x32x16_bf16 v[16:31], v[32:35], v[72:75], v[16:31]
	s_waitcnt lgkmcnt(0)
	v_mfma_f32_32x32x16_bf16 v[0:15], v[40:43], v[64:67], v[0:15]
	v_mfma_f32_32x32x16_bf16 v[16:31], v[36:39], v[76:79], v[16:31]
	ds_read_b128 v[32:35], v165 offset:4640
	ds_read_b128 v[36:39], v165 offset:4672
	s_waitcnt lgkmcnt(1)
	v_mfma_f32_32x32x16_bf16 v[0:15], v[32:35], v[68:71], v[0:15]
	ds_read_b128 v[32:35], v165 offset:4704
	s_nop 6
	s_nop 0
	s_nop 0
	s_nop 0
	s_nop 0
	s_nop 0
	s_nop 0
	s_waitcnt lgkmcnt(1)
	v_mfma_f32_32x32x16_bf16 v[0:15], v[36:39], v[72:75], v[0:15]
	s_nop 0
	s_nop 0
	s_nop 0
	s_nop 0
	s_nop 0
	s_nop 0
	s_nop 0
	s_waitcnt lgkmcnt(0)
	v_mfma_f32_32x32x16_bf16 v[0:15], v[32:35], v[76:79], v[0:15]
	ds_read_b128 v[200:203], v165 offset:9216
	ds_read_b128 v[204:207], v165 offset:13824
	ds_read_b128 v[214:217], v165 offset:9248
	ds_read_b128 v[218:221], v165 offset:13856
	ds_read_b128 v[222:225], v165 offset:9280
	ds_read_b128 v[226:229], v165 offset:13888
	ds_read_b128 v[230:233], v165 offset:9312
	ds_read_b128 v[234:237], v165 offset:13920
	v_max3_f32 v33, v16, s95, v17
	v_max3_f32 v33, v33, v18, v19
	v_max3_f32 v33, v33, v20, v21
	v_max3_f32 v33, v33, v22, v23
	v_max3_f32 v33, v33, v24, v25
	v_max3_f32 v33, v33, v26, v27
	s_nop 0
	v_max3_f32 v33, v33, v28, v29
	s_nop 0
	s_nop 0
	v_max3_f32 v33, v33, v30, v31
	s_nop 0
	s_nop 0
	s_nop 0
	v_max3_f32 v33, v33, v0, v1
	s_nop 0
	s_nop 0
	v_max3_f32 v33, v33, v2, v3
	s_nop 0
	s_nop 0
	v_max3_f32 v33, v33, v4, v5
	s_nop 0
	s_nop 0
	v_subrev_u32_e32 v32, s80, v57
	v_max3_f32 v33, v33, v6, v7
	s_nop 0
	s_nop 0
	v_cvt_f32_i32_e32 v32, v32
	v_max3_f32 v33, v33, v8, v9
	s_nop 0
	s_nop 0
	v_max3_f32 v33, v33, v10, v11
	s_nop 0
	s_nop 0
	v_max3_f32 v33, v33, v12, v13
	s_nop 0
	s_nop 0
	v_max3_f32 v33, v33, v14, v15
	v_cmp_lt_f32_e32 vcc, s76, v33
	v_fma_f32 v33, -v106, v32, v33
	s_nop 0
	v_cndmask_b32_e32 v33, v160, v33, vcc
	v_mov_b32_e32 v34, v33
	s_nop 1
	v_permlane32_swap_b32_e32 v34, v33
	s_nop 1
	s_waitcnt lgkmcnt(0)
; #define MFMA32(a, b, c) __builtin_amdgcn_mfma_f32_32x32x16_bf16((a), (b), (c), 0, 0, 0)
; template <int KSTRIDE, bool WIN, int MASK, int MODE>
; DI void attend_tile(const u16* Ks, const u16* Vts, const bf16x8 (&qf)[4], f32x16 (&O)[2], float& m, float& l, int dbase,
;                     float slope2, bool lanesel, float invl, unsigned* imp_row, int mbase, int lr, int hh) {
;     ...
;   mx = (mx > -1e29f) ? mx - ct : -1e30f;
;   mx = fmaxf(mx, __shfl_xor(mx, 32));
;   if (MASK == 2) mx = lanesel ? mx : -1e30f;
;   float mnew = m, alpha = 1.f;
;   if (MODE != 2) {
;     mnew = fmaxf(m, mx);
;     alpha = fexp2(m - mnew);
;     m = mnew;
;   }
;   float shift = mnew + ct;
;   if (MASK == 2) shift = lanesel ? shift : 1e30f;
;   float rs = 0.f;
; #pragma unroll
;   for (int kt = 0; kt < 2; ++kt)
; #pragma unroll
;     for (int e = 0; e < 16; ++e) {
;       float v = s[kt][e];
;       float pv;
;       if (MASK == 1) pv = (v > -1e29f) ? fexp2(v - shift) : 0.f;
;       else pv = fexp2(v - shift);
;       if (MODE == 2) pv *= invl;
;       s[kt][e] = pv;
;       rs += pv;
;     }
;   if (MODE != 2) l = l * alpha + rs;
;   if (MODE == 1) return;
;   if (MODE == 0) {
; #pragma unroll
;     for (int e = 0; e < 16; ++e) { O[0][e] *= alpha; O[1][e] *= alpha; }
;   }
;   if (MODE == 2) {
; #pragma unroll
;     for (int kt = 0; kt < 2; ++kt)
; #pragma unroll
;       for (int q4 = 0; q4 < 4; ++q4) {
;         float qsum = s[kt][q4 * 4] + s[kt][q4 * 4 + 1] + s[kt][q4 * 4 + 2] + s[kt][q4 * 4 + 3];
;         float last = s[kt][q4 * 4 + 3];
;         int mi = mbase + kt * 8 + 2 * q4 + hh;
;         atomicAdd(imp_row + mi, (unsigned)(qsum * 1048576.f + 0.5f));
;         if (mi + 1 < 64) atomicAdd(imp_row + mi + 1, (unsigned)(last * 1048576.f + 0.5f));
;       }
;   }
; #pragma unroll
;   for (int kt = 0; kt < 2; ++kt)
; #pragma unroll
;     for (int sx = 0; sx < 2; ++sx) {
;       unsigned pk[4];
; #pragma unroll
;       for (int q = 0; q < 4; ++q) pk[q] = pack2(s[kt][8 * sx + 2 * q], s[kt][8 * sx + 2 * q + 1]);
;       bf16x8 pb;
;       {
;         u32x4 t4 = {pk[0], pk[1], pk[2], pk[3]};
;         pb = __builtin_bit_cast(bf16x8, t4);
;       }
; #pragma unroll
;       for (int dt = 0; dt < 2; ++dt) {
;         bf16x8 a = *(const bf16x8*)(Vts + (dt * 32 + lr) * 72 + kt * 32 + 16 * sx + 8 * hh);
;         O[dt] = MFMA32(a, pb, O[dt]);
;       }
;     }
	v_max_f32_e32 v34, v34, v34
	v_max_f32_e32 v33, v33, v34
	v_cndmask_b32_e64 v33, v160, v33, s[0:1]
	v_max_f32_e32 v34, v169, v169
	v_max_f32_e32 v166, v34, v33
	v_fma_f32 v32, v106, v32, v166
	v_cndmask_b32_e64 v32, v155, v32, s[0:1]
	v_sub_f32_e32 v16, v16, v32
	v_exp_f32_e32 v34, v16
	v_sub_f32_e32 v17, v17, v32
	v_exp_f32_e32 v35, v17
	v_sub_f32_e32 v17, v18, v32
	v_exp_f32_e32 v173, v17
	v_sub_f32_e32 v17, v19, v32
	v_exp_f32_e32 v174, v17
	v_sub_f32_e32 v17, v20, v32
	v_sub_f32_e32 v1, v1, v32
	v_add_f32_e32 v16, 0, v34
	v_exp_f32_e32 v175, v17
	v_sub_f32_e32 v17, v21, v32
	v_exp_f32_e32 v37, v1
	v_sub_f32_e32 v1, v2, v32
	v_add_f32_e32 v16, v35, v16
	v_exp_f32_e32 v176, v17
	v_sub_f32_e32 v17, v22, v32
	v_exp_f32_e32 v38, v1
	v_sub_f32_e32 v1, v3, v32
	v_add_f32_e32 v16, v173, v16
	v_exp_f32_e32 v177, v17
	v_sub_f32_e32 v17, v23, v32
	v_exp_f32_e32 v39, v1
	v_sub_f32_e32 v1, v4, v32
	v_add_f32_e32 v16, v174, v16
	v_exp_f32_e32 v178, v17
	v_sub_f32_e32 v17, v24, v32
	v_exp_f32_e32 v40, v1
	v_sub_f32_e32 v1, v5, v32
	v_add_f32_e32 v16, v175, v16
	v_exp_f32_e32 v51, v17
	v_sub_f32_e32 v17, v25, v32
	v_exp_f32_e32 v41, v1
	v_sub_f32_e32 v1, v6, v32
	v_add_f32_e32 v16, v176, v16
	v_exp_f32_e32 v53, v17
	v_sub_f32_e32 v17, v26, v32
	v_exp_f32_e32 v42, v1
	v_sub_f32_e32 v1, v7, v32
	v_add_f32_e32 v16, v177, v16
	v_exp_f32_e32 v54, v17
	v_sub_f32_e32 v17, v27, v32
	v_exp_f32_e32 v44, v1
	v_sub_f32_e32 v1, v8, v32
	v_add_f32_e32 v16, v178, v16
	v_exp_f32_e32 v55, v17
	v_sub_f32_e32 v17, v28, v32
	v_exp_f32_e32 v43, v1
	v_sub_f32_e32 v1, v9, v32
	v_sub_f32_e32 v33, v169, v166
	v_add_f32_e32 v16, v51, v16
	v_exp_f32_e32 v169, v17
	v_sub_f32_e32 v17, v29, v32
	v_exp_f32_e32 v45, v1
	v_sub_f32_e32 v1, v10, v32
	v_add_f32_e32 v16, v53, v16
	v_exp_f32_e32 v170, v17
	v_sub_f32_e32 v17, v30, v32
	v_exp_f32_e32 v46, v1
	v_sub_f32_e32 v1, v11, v32
	v_add_f32_e32 v16, v54, v16
	v_exp_f32_e32 v171, v17
	v_sub_f32_e32 v17, v31, v32
	v_exp_f32_e32 v47, v1
	v_sub_f32_e32 v1, v12, v32
	v_add_f32_e32 v16, v55, v16
	v_exp_f32_e32 v172, v17
	v_sub_f32_e32 v0, v0, v32
	v_exp_f32_e32 v48, v1
	v_sub_f32_e32 v1, v13, v32
	v_add_f32_e32 v16, v169, v16
	v_exp_f32_e32 v36, v0
	v_exp_f32_e32 v49, v1
	v_sub_f32_e32 v1, v14, v32
	v_exp_f32_e32 v14, v33
	v_add_f32_e32 v16, v170, v16
	v_add_f32_e32 v16, v171, v16
	v_add_f32_e32 v16, v172, v16
	v_add_f32_e32 v0, v36, v16
	v_pk_mul_f32 v[16:17], v[122:123], v[14:15] op_sel_hi:[1,0]
	v_pk_mul_f32 v[18:19], v[124:125], v[14:15] op_sel_hi:[1,0]
	s_nop 0
	v_add_f32_e32 v0, v37, v0
	v_add_f32_e32 v0, v38, v0
	v_add_f32_e32 v0, v39, v0
	v_add_f32_e32 v0, v40, v0
	v_add_f32_e32 v0, v41, v0
	v_add_f32_e32 v0, v42, v0
	v_add_f32_e32 v0, v44, v0
	v_exp_f32_e32 v50, v1
	v_sub_f32_e32 v1, v15, v32
	v_pk_mul_f32 v[20:21], v[126:127], v[14:15] op_sel_hi:[1,0]
	v_pk_mul_f32 v[22:23], v[128:129], v[14:15] op_sel_hi:[1,0]
	v_pk_mul_f32 v[24:25], v[130:131], v[14:15] op_sel_hi:[1,0]
	v_pk_mul_f32 v[26:27], v[132:133], v[14:15] op_sel_hi:[1,0]
	v_pk_mul_f32 v[28:29], v[134:135], v[14:15] op_sel_hi:[1,0]
	v_pk_mul_f32 v[30:31], v[136:137], v[14:15] op_sel_hi:[1,0]
	v_cvt_pk_bf16_f32 v32, v34, v35
	v_cvt_pk_bf16_f32 v33, v173, v174
	v_cvt_pk_bf16_f32 v34, v175, v176
	v_cvt_pk_bf16_f32 v35, v177, v178
	v_add_f32_e32 v0, v43, v0
	v_add_f32_e32 v0, v45, v0
	s_waitcnt lgkmcnt(0)
	v_mfma_f32_32x32x16_bf16 v[16:31], v[200:203], v[32:35], v[16:31]
	s_nop 0
	v_add_f32_e32 v0, v46, v0
	v_add_f32_e32 v0, v47, v0
	v_exp_f32_e32 v52, v1
	v_add_f32_e32 v0, v48, v0
	v_add_f32_e32 v0, v49, v0
	v_add_f32_e32 v0, v50, v0
	v_add_f32_e32 v167, v52, v0
	v_fmac_f32_e32 v167, v168, v14
	v_pk_mul_f32 v[0:1], v[138:139], v[14:15] op_sel_hi:[1,0]
	v_pk_mul_f32 v[2:3], v[140:141], v[14:15] op_sel_hi:[1,0]
	v_pk_mul_f32 v[4:5], v[142:143], v[14:15] op_sel_hi:[1,0]
	v_pk_mul_f32 v[6:7], v[144:145], v[14:15] op_sel_hi:[1,0]
	v_pk_mul_f32 v[8:9], v[146:147], v[14:15] op_sel_hi:[1,0]
	v_pk_mul_f32 v[10:11], v[148:149], v[14:15] op_sel_hi:[1,0]
	v_pk_mul_f32 v[12:13], v[150:151], v[14:15] op_sel_hi:[1,0]
	v_pk_mul_f32 v[14:15], v[152:153], v[14:15] op_sel_hi:[1,0]
	s_waitcnt lgkmcnt(0)
	s_nop 0
	v_mfma_f32_32x32x16_bf16 v[0:15], v[204:207], v[32:35], v[0:15]
	s_nop 0
	v_cvt_pk_bf16_f32 v32, v51, v53
	v_cvt_pk_bf16_f32 v33, v54, v55
	v_cvt_pk_bf16_f32 v34, v169, v170
	v_cvt_pk_bf16_f32 v35, v171, v172
	s_waitcnt lgkmcnt(0)
	s_nop 0
	v_mfma_f32_32x32x16_bf16 v[16:31], v[214:217], v[32:35], v[16:31]
	s_nop 0
	s_waitcnt lgkmcnt(0)
	v_mfma_f32_32x32x16_bf16 v[0:15], v[218:221], v[32:35], v[0:15]
	v_cvt_pk_bf16_f32 v32, v36, v37
	v_cvt_pk_bf16_f32 v33, v38, v39
	s_nop 0
	v_cvt_pk_bf16_f32 v34, v40, v41
	v_cvt_pk_bf16_f32 v35, v42, v44
	s_waitcnt lgkmcnt(0)
	s_nop 0
	v_mfma_f32_32x32x16_bf16 v[16:31], v[222:225], v[32:35], v[16:31]
	s_nop 0
	s_waitcnt lgkmcnt(0)
	v_mfma_f32_32x32x16_bf16 v[0:15], v[226:229], v[32:35], v[0:15]
	s_nop 0
	v_cvt_pk_bf16_f32 v32, v43, v45
	v_cvt_pk_bf16_f32 v33, v46, v47
	v_cvt_pk_bf16_f32 v34, v48, v49
	v_cvt_pk_bf16_f32 v35, v50, v52
	s_waitcnt lgkmcnt(0)
	s_nop 0
	v_mfma_f32_32x32x16_bf16 v[16:31], v[230:233], v[32:35], v[16:31]
	s_nop 0
	s_waitcnt lgkmcnt(0)
	v_mfma_f32_32x32x16_bf16 v[0:15], v[234:237], v[32:35], v[0:15]
	s_nop 7
	s_nop 3
